# LayerNorm phases: butterfly all-reduce via DPP + permlane16/32 swaps instead of ds_bpermute; phase-5 row loop prefetches two rows ahead
# baseline (speedup 1.0000x reference)
; DI void phase_ln(Frame& F, const float* g, const float* b, bool lazy) {
;     const int gw = F.bid * NWAVES + F.wave, NGW = F.G * NWAVES;
;     bf16* xb = (bf16*)(F.ws + WS_XB); float* lnst = (float*)(F.ws + WS_LNST);
;     f32x4 gv[8], bv[8];
; #pragma unroll
;     for (int j = 0; j < 8; ++j) { gv[j] = *(const f32x4*)(g + 256 * j + 4 * F.lane); bv[j] = *(const f32x4*)(b + 256 * j + 4 * F.lane); }
;     f32x4 vn[8];
;     if (gw < MTOK) {
; #pragma unroll
;         for (int j = 0; j < 8; ++j) vn[j] = *(const f32x4*)(F.out + (size_t)gw * DM + 4 * F.lane + 256 * j); }
.LBB0_665:
	s_cmp_lt_i32 s80, 6
	s_cselect_b64 s[4:5], -1, 0
	s_and_b64 s[6:7], s[4:5], s[0:1]
	s_andn2_b64 vcc, exec, s[6:7]
	s_cbranch_vccnz .LBB0_673
	s_lshl_b32 s0, s84, 3
	s_add_i32 s8, s0, s82
	s_cmpk_gt_i32 s8, 0x3fff
	s_cbranch_scc1 .LBB0_673
	v_readlane_b32 s36, v231, 2
	s_waitcnt vmcnt(0)
	v_lshlrev_b32_e32 v128, 4, v144
	v_mov_b32_e32 v129, 0
	v_readlane_b32 s48, v231, 14
	v_readlane_b32 s49, v231, 15
	s_lshl_b32 s10, s18, 3
	s_add_u32 s3, s22, 0x1100000
	v_lshl_add_u64 v[32:33], s[48:49], 0, v[128:129]
	v_readlane_b32 s50, v231, 16
	v_readlane_b32 s51, v231, 17
	v_add_co_u32_e32 v56, vcc, 0x1000, v32
	s_addc_u32 s30, s23, 0
	s_ashr_i32 s9, s8, 31
	v_lshl_add_u64 v[34:35], s[50:51], 0, v[128:129]
	global_load_dwordx4 v[0:3], v128, s[48:49]
	global_load_dwordx4 v[4:7], v128, s[50:51]
	s_waitcnt lgkmcnt(6)
	global_load_dwordx4 v[8:11], v128, s[48:49] offset:1024
	s_waitcnt lgkmcnt(4)
	global_load_dwordx4 v[12:15], v128, s[50:51] offset:1024
	s_waitcnt lgkmcnt(2)
	global_load_dwordx4 v[16:19], v128, s[48:49] offset:2048
	s_waitcnt lgkmcnt(0)
	global_load_dwordx4 v[20:23], v128, s[50:51] offset:2048
	global_load_dwordx4 v[24:27], v128, s[48:49] offset:3072
	global_load_dwordx4 v[28:31], v128, s[50:51] offset:3072
	v_addc_co_u32_e32 v57, vcc, 0, v33, vcc
	s_lshl_b64 s[4:5], s[8:9], 13
	v_add_co_u32_e32 v60, vcc, 0x1000, v34
	s_add_u32 s0, s20, s4
	s_nop 0
	v_addc_co_u32_e32 v61, vcc, 0, v35, vcc
	global_load_dwordx4 v[32:35], v[56:57], off
	global_load_dwordx4 v[36:39], v[56:57], off offset:1024
	global_load_dwordx4 v[40:43], v[60:61], off
	global_load_dwordx4 v[44:47], v[60:61], off offset:1024
	global_load_dwordx4 v[48:51], v[56:57], off offset:2048
	global_load_dwordx4 v[52:55], v[56:57], off offset:3072
	s_addc_u32 s1, s21, s5
	s_movk_i32 s11, 0x1000
	v_lshl_add_u64 v[56:57], s[0:1], 0, v[128:129]
	v_add_co_u32_e32 v56, vcc, s11, v56
	v_mbcnt_lo_u32_b32 v80, -1, 0
	s_nop 0
	v_addc_co_u32_e32 v57, vcc, 0, v57, vcc
	global_load_dwordx4 v[68:71], v[56:57], off offset:2048
	global_load_dwordx4 v[64:67], v[56:57], off offset:3072
	global_load_dwordx4 v[76:79], v[56:57], off
	global_load_dwordx4 v[72:75], v[56:57], off offset:1024
	global_load_dwordx4 v[116:119], v128, s[0:1] offset:2048
	global_load_dwordx4 v[112:115], v128, s[0:1] offset:3072
	global_load_dwordx4 v[124:127], v128, s[0:1]
	global_load_dwordx4 v[120:123], v128, s[0:1] offset:1024
	s_nop 0
	global_load_dwordx4 v[56:59], v[60:61], off offset:2048
	s_nop 0
	global_load_dwordx4 v[60:63], v[60:61], off offset:3072
	v_mbcnt_hi_u32_b32 v80, -1, v80
	v_and_b32_e32 v81, 64, v80
	v_add_u32_e32 v81, 64, v81
	v_xor_b32_e32 v82, 1, v80
	v_cmp_lt_i32_e32 vcc, v82, v81
	s_ashr_i32 s11, s10, 31
	s_lshl_b32 s14, s84, 4
	v_cndmask_b32_e32 v82, v80, v82, vcc
	v_lshlrev_b32_e32 v134, 2, v82
	v_xor_b32_e32 v82, 2, v80
	v_cmp_lt_i32_e32 vcc, v82, v81
	s_lshl_b32 s15, s82, 1
	s_lshl_b64 s[12:13], s[10:11], 13
	v_cndmask_b32_e32 v82, v80, v82, vcc
	v_lshlrev_b32_e32 v135, 2, v82
	v_xor_b32_e32 v82, 4, v80
	v_cmp_lt_i32_e32 vcc, v82, v81
	s_add_i32 s14, s14, s15
	s_lshl_b32 s31, s18, 4
	v_cndmask_b32_e32 v82, v80, v82, vcc
	v_lshlrev_b32_e32 v136, 2, v82
	v_xor_b32_e32 v82, 8, v80
	v_cmp_lt_i32_e32 vcc, v82, v81
	s_lshl_b64 s[16:17], s[8:9], 12
	s_add_u32 s16, s22, s16
	v_cndmask_b32_e32 v82, v80, v82, vcc
	v_lshlrev_b32_e32 v137, 2, v82
	v_xor_b32_e32 v82, 16, v80
	v_cmp_lt_i32_e32 vcc, v82, v81
	s_addc_u32 s17, s23, s17
	v_cmp_eq_u32_e64 s[0:1], 0, v144
	v_cndmask_b32_e32 v82, v80, v82, vcc
	v_lshlrev_b32_e32 v138, 2, v82
	v_xor_b32_e32 v82, 32, v80
	v_cmp_lt_i32_e32 vcc, v82, v81
	v_mov_b32_e32 v81, v129
	v_mov_b32_e32 v140, 0x3727c5ac
	v_cndmask_b32_e32 v80, v80, v82, vcc
	v_lshlrev_b32_e32 v139, 2, v80
	v_lshlrev_b32_e32 v80, 3, v144
	v_lshl_add_u64 v[80:81], s[16:17], 0, v[80:81]
	s_mov_b64 s[16:17], 0x7800000
	v_lshl_add_u64 v[130:131], v[80:81], 0, s[16:17]
	s_lshl_b64 s[16:17], s[10:11], 12
	s_add_u32 s4, s12, s4
	s_addc_u32 s5, s13, s5
	s_add_u32 s4, s20, s4
	s_addc_u32 s5, s21, s5
	v_lshl_add_u64 v[80:81], s[4:5], 0, v[128:129]
	s_mov_b64 s[4:5], 0x1000
	v_lshl_add_u64 v[132:133], v[80:81], 0, s[4:5]
	s_mov_b32 s9, 0xf800000
	v_mov_b32_e32 v141, 0x260
	v_readlane_b32 s37, v231, 3
	v_readlane_b32 s38, v231, 4
	v_readlane_b32 s39, v231, 5
	v_readlane_b32 s40, v231, 6
	v_readlane_b32 s41, v231, 7
	v_readlane_b32 s42, v231, 8
	v_readlane_b32 s43, v231, 9
	v_readlane_b32 s44, v231, 10
	v_readlane_b32 s45, v231, 11
	v_readlane_b32 s46, v231, 12
	v_readlane_b32 s47, v231, 13
	s_waitcnt vmcnt(9)
	v_mov_b64_e32 v[86:87], v[70:71]
	s_waitcnt vmcnt(8)
	v_mov_b64_e32 v[82:83], v[66:67]
	s_waitcnt vmcnt(7)
	v_mov_b64_e32 v[94:95], v[78:79]
	s_waitcnt vmcnt(6)
	v_mov_b64_e32 v[90:91], v[74:75]
	s_waitcnt vmcnt(5)
	v_mov_b64_e32 v[100:101], v[116:117]
	s_waitcnt vmcnt(4)
	v_mov_b64_e32 v[96:97], v[112:113]
	s_waitcnt vmcnt(3)
	v_mov_b64_e32 v[108:109], v[124:125]
	s_waitcnt vmcnt(2)
	v_mov_b64_e32 v[104:105], v[120:121]
	v_mov_b64_e32 v[80:81], v[64:65]
	v_mov_b64_e32 v[84:85], v[68:69]
	v_mov_b64_e32 v[88:89], v[72:73]
	v_mov_b64_e32 v[92:93], v[76:77]
	v_mov_b64_e32 v[98:99], v[114:115]
	v_mov_b64_e32 v[102:103], v[118:119]
	v_mov_b64_e32 v[106:107], v[122:123]
	v_mov_b64_e32 v[110:111], v[126:127]
	s_mov_b32 s99, 0
	s_add_i32 s8, s8, s10
	s_cmpk_gt_i32 s8, 0x3fff
	s_cbranch_scc1 .Lln5_p1
	global_load_dwordx4 v[108:111], v[132:133], off offset:-4096
	global_load_dwordx4 v[104:107], v[132:133], off offset:-3072
	global_load_dwordx4 v[100:103], v[132:133], off offset:-2048
	global_load_dwordx4 v[96:99], v[132:133], off offset:-1024
	global_load_dwordx4 v[92:95], v[132:133], off
	global_load_dwordx4 v[88:91], v[132:133], off offset:1024
	global_load_dwordx4 v[84:87], v[132:133], off offset:2048
	global_load_dwordx4 v[80:83], v[132:133], off offset:3072
; DI unsigned cvtpk(float lo, float hi) { f32x2_t v = {lo, hi}; bf16x2_t b = __builtin_convertvector(v, bf16x2_t); return __builtin_bit_cast(unsigned, b); }
; DI void phase_ln(Frame& F, const float* g, const float* b, bool lazy) {
;     ...
;         if (row + NGW < MTOK) {
; #pragma unroll
;             for (int j = 0; j < 8; ++j) vn[j] = *(const f32x4*)(xr + (size_t)NGW * DM + 256 * j); }
;         const float mean = wave_sum(s) * (1.f / DM); float s2 = 0.f;
; #pragma unroll
;         for (int j = 0; j < 8; ++j) { v[j] = v[j] - mean; s2 += (v[j][0] * v[j][0] + v[j][1] * v[j][1]) + (v[j][2] * v[j][2] + v[j][3] * v[j][3]); }
;         const float rstd = 1.f / sqrtf(wave_sum(s2) * (1.f / DM) + LN_EPS);
;         if (lazy && F.lane == 0) { lnst[2 * row] = mean; lnst[2 * row + 1] = rstd; }
; #pragma unroll
;         for (int j = 0; j < 8; ++j) { const f32x4 y = v[j] * rstd * gv[j] + bv[j];
;             if (lazy) { u32x2 o; o.x = cvtpk(y[0], y[1]); o.y = cvtpk(y[2], y[3]); *(u32x2*)(xb + (size_t)row * DM + 256 * j + 4 * F.lane) = o; }
;             else __builtin_nontemporal_store(y, (f32x4*)(xr + 256 * j)); }
.Lln5_p1:
	v_lshl_add_u64 v[132:133], v[132:133], 0, s[12:13]
	s_branch .LBB0_669
.LBB0_668:
	s_or_b64 exec, exec, s[4:5]
	v_pk_mul_f32 v[126:127], v[126:127], v[128:129] op_sel_hi:[1,0]
	v_pk_mul_f32 v[124:125], v[124:125], v[128:129] op_sel_hi:[1,0]
	v_pk_mul_f32 v[122:123], v[122:123], v[128:129] op_sel_hi:[1,0]
	v_pk_mul_f32 v[120:121], v[120:121], v[128:129] op_sel_hi:[1,0]
	v_pk_mul_f32 v[118:119], v[118:119], v[128:129] op_sel_hi:[1,0]
	v_pk_mul_f32 v[116:117], v[116:117], v[128:129] op_sel_hi:[1,0]
	v_pk_mul_f32 v[114:115], v[114:115], v[128:129] op_sel_hi:[1,0]
	v_pk_mul_f32 v[112:113], v[112:113], v[128:129] op_sel_hi:[1,0]
	v_pk_mul_f32 v[78:79], v[78:79], v[128:129] op_sel_hi:[1,0]
	v_pk_mul_f32 v[76:77], v[76:77], v[128:129] op_sel_hi:[1,0]
	v_pk_mul_f32 v[74:75], v[74:75], v[128:129] op_sel_hi:[1,0]
	v_pk_mul_f32 v[72:73], v[72:73], v[128:129] op_sel_hi:[1,0]
	v_pk_mul_f32 v[70:71], v[70:71], v[128:129] op_sel_hi:[1,0]
	v_pk_mul_f32 v[68:69], v[68:69], v[128:129] op_sel_hi:[1,0]
	v_pk_mul_f32 v[66:67], v[66:67], v[128:129] op_sel_hi:[1,0]
	v_pk_mul_f32 v[64:65], v[64:65], v[128:129] op_sel_hi:[1,0]
	v_pk_fma_f32 v[126:127], v[2:3], v[126:127], v[6:7]
	v_pk_fma_f32 v[124:125], v[0:1], v[124:125], v[4:5]
	v_pk_fma_f32 v[122:123], v[10:11], v[122:123], v[14:15]
	v_pk_fma_f32 v[120:121], v[8:9], v[120:121], v[12:13]
	v_pk_fma_f32 v[118:119], v[18:19], v[118:119], v[22:23]
	v_pk_fma_f32 v[116:117], v[16:17], v[116:117], v[20:21]
	v_pk_fma_f32 v[114:115], v[26:27], v[114:115], v[30:31]
	v_pk_fma_f32 v[112:113], v[24:25], v[112:113], v[28:29]
	v_pk_fma_f32 v[78:79], v[34:35], v[78:79], v[42:43]
	v_pk_fma_f32 v[76:77], v[32:33], v[76:77], v[40:41]
	v_pk_fma_f32 v[74:75], v[38:39], v[74:75], v[46:47]
	v_pk_fma_f32 v[72:73], v[36:37], v[72:73], v[44:45]
	s_waitcnt vmcnt(9)
	v_pk_fma_f32 v[70:71], v[50:51], v[70:71], v[58:59]
	v_pk_fma_f32 v[68:69], v[48:49], v[68:69], v[56:57]
	v_pk_fma_f32 v[66:67], v[54:55], v[66:67], v[62:63]
	v_pk_fma_f32 v[64:65], v[52:53], v[64:65], v[60:61]
	v_cvt_pk_bf16_f32 v124, v124, v125
	v_cvt_pk_bf16_f32 v125, v126, v127
	v_cvt_pk_bf16_f32 v120, v120, v121
	v_cvt_pk_bf16_f32 v121, v122, v123
	v_cvt_pk_bf16_f32 v116, v116, v117
	v_cvt_pk_bf16_f32 v117, v118, v119
	v_cvt_pk_bf16_f32 v112, v112, v113
	v_cvt_pk_bf16_f32 v113, v114, v115
	v_cvt_pk_bf16_f32 v76, v76, v77
	v_cvt_pk_bf16_f32 v77, v78, v79
	v_cvt_pk_bf16_f32 v72, v72, v73
	v_cvt_pk_bf16_f32 v73, v74, v75
	v_cvt_pk_bf16_f32 v68, v68, v69
	v_cvt_pk_bf16_f32 v69, v70, v71
	v_cvt_pk_bf16_f32 v64, v64, v65
	v_cvt_pk_bf16_f32 v65, v66, v67
	global_store_dwordx2 v[130:131], v[124:125], off
	global_store_dwordx2 v[130:131], v[120:121], off offset:512
	global_store_dwordx2 v[130:131], v[116:117], off offset:1024
	global_store_dwordx2 v[130:131], v[112:113], off offset:1536
	global_store_dwordx2 v[130:131], v[76:77], off offset:2048
	global_store_dwordx2 v[130:131], v[72:73], off offset:2560
	global_store_dwordx2 v[130:131], v[68:69], off offset:3072
	global_store_dwordx2 v[130:131], v[64:65], off offset:3584
	s_cmp_lg_u32 s99, 0
	s_cbranch_scc1 .Lln5_cpB
	v_mov_b64_e32 v[64:65], v[80:81]
	v_mov_b64_e32 v[68:69], v[84:85]
	v_mov_b64_e32 v[72:73], v[88:89]
	v_mov_b64_e32 v[76:77], v[92:93]
	v_mov_b64_e32 v[114:115], v[98:99]
	v_mov_b64_e32 v[118:119], v[102:103]
	v_mov_b64_e32 v[122:123], v[106:107]
	v_mov_b64_e32 v[126:127], v[110:111]
	v_mov_b64_e32 v[66:67], v[82:83]
	v_mov_b64_e32 v[70:71], v[86:87]
	v_mov_b64_e32 v[74:75], v[90:91]
	v_mov_b64_e32 v[78:79], v[94:95]
	v_mov_b64_e32 v[112:113], v[96:97]
	v_mov_b64_e32 v[116:117], v[100:101]
	v_mov_b64_e32 v[120:121], v[104:105]
	v_mov_b64_e32 v[124:125], v[108:109]
	s_branch .Lln5_cpd
.Lln5_cpB:
	v_mov_b64_e32 v[64:65], v[152:153]
	v_mov_b64_e32 v[68:69], v[156:157]
	v_mov_b64_e32 v[72:73], v[160:161]
	v_mov_b64_e32 v[76:77], v[164:165]
	v_mov_b64_e32 v[114:115], v[170:171]
	v_mov_b64_e32 v[118:119], v[180:181]
	v_mov_b64_e32 v[122:123], v[184:185]
	v_mov_b64_e32 v[126:127], v[188:189]
	v_mov_b64_e32 v[66:67], v[154:155]
	v_mov_b64_e32 v[70:71], v[158:159]
	v_mov_b64_e32 v[74:75], v[162:163]
	v_mov_b64_e32 v[78:79], v[166:167]
	v_mov_b64_e32 v[112:113], v[168:169]
	v_mov_b64_e32 v[116:117], v[178:179]
	v_mov_b64_e32 v[120:121], v[182:183]
	v_mov_b64_e32 v[124:125], v[186:187]
.Lln5_cpd:
	s_xor_b32 s99, s99, 1
	s_add_i32 s14, s14, s31
	v_lshl_add_u64 v[130:131], v[130:131], 0, s[16:17]
	v_lshl_add_u64 v[132:133], v[132:133], 0, s[12:13]
	s_andn2_b64 vcc, exec, s[28:29]
	s_cbranch_vccz .LBB0_673
.LBB0_669:
	s_cmpk_gt_i32 s8, 0x3fff
	s_cselect_b64 s[28:29], -1, 0
	s_add_i32 s8, s8, s10
	s_cmpk_gt_i32 s8, 0x3fff
	s_cbranch_scc1 .LBB0_671
	s_cmp_lg_u32 s99, 0
	s_cbranch_scc1 .Lln5_ldA
	global_load_dwordx4 v[186:189], v[132:133], off offset:-4096
	global_load_dwordx4 v[182:185], v[132:133], off offset:-3072
	global_load_dwordx4 v[178:181], v[132:133], off offset:-2048
	global_load_dwordx4 v[168:171], v[132:133], off offset:-1024
	global_load_dwordx4 v[164:167], v[132:133], off
	global_load_dwordx4 v[160:163], v[132:133], off offset:1024
	global_load_dwordx4 v[156:159], v[132:133], off offset:2048
	global_load_dwordx4 v[152:155], v[132:133], off offset:3072
	s_branch .LBB0_671
.Lln5_ldA:
	global_load_dwordx4 v[108:111], v[132:133], off offset:-4096
	global_load_dwordx4 v[104:107], v[132:133], off offset:-3072
	global_load_dwordx4 v[100:103], v[132:133], off offset:-2048
	global_load_dwordx4 v[96:99], v[132:133], off offset:-1024
	global_load_dwordx4 v[92:95], v[132:133], off
	global_load_dwordx4 v[88:91], v[132:133], off offset:1024
	global_load_dwordx4 v[84:87], v[132:133], off offset:2048
	global_load_dwordx4 v[80:83], v[132:133], off offset:3072
; DI void phase_ln(Frame& F, const float* g, const float* b, bool lazy) {
;     ...
;         for (int j = 0; j < 8; ++j) { v[j] = vn[j]; s += (v[j][0] + v[j][1]) + (v[j][2] + v[j][3]); }
;         if (row + NGW < MTOK) {
; #pragma unroll
;             for (int j = 0; j < 8; ++j) vn[j] = *(const f32x4*)(xr + (size_t)NGW * DM + 256 * j); }
;         const float mean = wave_sum(s) * (1.f / DM); float s2 = 0.f;
; #pragma unroll
;         for (int j = 0; j < 8; ++j) { v[j] = v[j] - mean; s2 += (v[j][0] * v[j][0] + v[j][1] * v[j][1]) + (v[j][2] * v[j][2] + v[j][3] * v[j][3]); }
;         const float rstd = 1.f / sqrtf(wave_sum(s2) * (1.f / DM) + LN_EPS);
;         if (lazy && F.lane == 0) { lnst[2 * row] = mean; lnst[2 * row + 1] = rstd; }
.LBB0_671:
	v_add_f32_e32 v128, v124, v125
	v_add_f32_e32 v142, v126, v127
	v_add_f32_e32 v128, v128, v142
	v_add_f32_e32 v142, v120, v121
	v_add_f32_e32 v143, v122, v123
	v_add_f32_e32 v128, 0, v128
	v_add_f32_e32 v142, v142, v143
	v_add_f32_e32 v128, v142, v128
	v_add_f32_e32 v142, v116, v117
	v_add_f32_e32 v143, v118, v119
	v_add_f32_e32 v142, v142, v143
	v_add_f32_e32 v128, v142, v128
	v_add_f32_e32 v142, v112, v113
	v_add_f32_e32 v143, v114, v115
	v_add_f32_e32 v142, v142, v143
	v_add_f32_e32 v128, v142, v128
	v_add_f32_e32 v142, v76, v77
	v_add_f32_e32 v143, v78, v79
	v_add_f32_e32 v142, v142, v143
	v_add_f32_e32 v128, v142, v128
	v_add_f32_e32 v142, v72, v73
	v_add_f32_e32 v143, v74, v75
	v_add_f32_e32 v142, v142, v143
	v_add_f32_e32 v128, v142, v128
	v_add_f32_e32 v142, v68, v69
	v_add_f32_e32 v143, v70, v71
	v_add_f32_e32 v142, v142, v143
	v_add_f32_e32 v128, v142, v128
	v_add_f32_e32 v142, v64, v65
	v_add_f32_e32 v143, v66, v67
	v_add_f32_e32 v142, v142, v143
	v_add_f32_e32 v128, v142, v128
	s_nop 1
	v_add_f32_dpp v128, v128, v128 quad_perm:[1,0,3,2] row_mask:0xf bank_mask:0xf
	s_nop 1
	v_add_f32_dpp v128, v128, v128 quad_perm:[2,3,0,1] row_mask:0xf bank_mask:0xf
	s_nop 1
	v_add_f32_dpp v128, v128, v128 row_half_mirror row_mask:0xf bank_mask:0xf
	s_nop 1
	v_add_f32_dpp v128, v128, v128 row_mirror row_mask:0xf bank_mask:0xf
	v_mov_b32_e32 v142, v128
	s_nop 1
	v_permlane16_swap_b32_e32 v128, v142
	v_add_f32_e32 v128, v128, v142
	v_mov_b32_e32 v142, v128
	s_nop 1
	v_permlane32_swap_b32_e32 v128, v142
	v_add_f32_e32 v142, v128, v142
	v_fmamk_f32 v127, v142, 0xba000000, v127
	v_fmamk_f32 v125, v142, 0xba000000, v125
	v_fmamk_f32 v126, v142, 0xba000000, v126
	v_fmac_f32_e32 v124, 0xba000000, v142
	v_mul_f32_e32 v128, v125, v125
	v_mul_f32_e32 v143, v127, v127
	v_fmac_f32_e32 v128, v124, v124
	v_fmac_f32_e32 v143, v126, v126
	v_fmamk_f32 v123, v142, 0xba000000, v123
	v_fmamk_f32 v121, v142, 0xba000000, v121
	v_add_f32_e32 v128, v128, v143
	v_fmamk_f32 v122, v142, 0xba000000, v122
	v_fmac_f32_e32 v120, 0xba000000, v142
	v_mul_f32_e32 v143, v121, v121
	v_mul_f32_e32 v145, v123, v123
	v_fmac_f32_e32 v143, v120, v120
	v_fmac_f32_e32 v145, v122, v122
	v_add_f32_e32 v143, v143, v145
	v_fmamk_f32 v119, v142, 0xba000000, v119
	v_fmamk_f32 v117, v142, 0xba000000, v117
	v_add_f32_e32 v128, v128, v143
	v_fmamk_f32 v118, v142, 0xba000000, v118
	v_fmac_f32_e32 v116, 0xba000000, v142
	v_mul_f32_e32 v143, v117, v117
	v_mul_f32_e32 v145, v119, v119
	v_fmac_f32_e32 v143, v116, v116
	v_fmac_f32_e32 v145, v118, v118
	v_add_f32_e32 v143, v143, v145
	v_fmamk_f32 v115, v142, 0xba000000, v115
	v_fmamk_f32 v113, v142, 0xba000000, v113
	v_add_f32_e32 v128, v143, v128
	v_fmamk_f32 v114, v142, 0xba000000, v114
	v_fmac_f32_e32 v112, 0xba000000, v142
	v_mul_f32_e32 v143, v113, v113
	v_mul_f32_e32 v145, v115, v115
	v_fmac_f32_e32 v143, v112, v112
	v_fmac_f32_e32 v145, v114, v114
	v_add_f32_e32 v143, v143, v145
	v_fmamk_f32 v79, v142, 0xba000000, v79
	v_fmamk_f32 v77, v142, 0xba000000, v77
	v_add_f32_e32 v128, v143, v128
	v_fmamk_f32 v78, v142, 0xba000000, v78
	v_fmac_f32_e32 v76, 0xba000000, v142
	v_mul_f32_e32 v143, v77, v77
	v_mul_f32_e32 v145, v79, v79
	v_fmac_f32_e32 v143, v76, v76
	v_fmac_f32_e32 v145, v78, v78
	v_add_f32_e32 v143, v143, v145
	v_fmamk_f32 v75, v142, 0xba000000, v75
	v_fmamk_f32 v73, v142, 0xba000000, v73
	v_add_f32_e32 v128, v143, v128
	v_fmamk_f32 v74, v142, 0xba000000, v74
	v_fmac_f32_e32 v72, 0xba000000, v142
	v_mul_f32_e32 v143, v73, v73
	v_mul_f32_e32 v145, v75, v75
	v_fmac_f32_e32 v143, v72, v72
	v_fmac_f32_e32 v145, v74, v74
	v_add_f32_e32 v143, v143, v145
	v_fmamk_f32 v71, v142, 0xba000000, v71
	v_fmamk_f32 v69, v142, 0xba000000, v69
	v_add_f32_e32 v128, v143, v128
	v_fmamk_f32 v70, v142, 0xba000000, v70
	v_fmac_f32_e32 v68, 0xba000000, v142
	v_mul_f32_e32 v143, v69, v69
	v_mul_f32_e32 v145, v71, v71
	v_fmac_f32_e32 v143, v68, v68
	v_fmac_f32_e32 v145, v70, v70
	v_add_f32_e32 v143, v143, v145
	v_fmamk_f32 v67, v142, 0xba000000, v67
	v_fmamk_f32 v65, v142, 0xba000000, v65
	v_add_f32_e32 v128, v143, v128
	v_fmamk_f32 v66, v142, 0xba000000, v66
	v_fmac_f32_e32 v64, 0xba000000, v142
	v_mul_f32_e32 v143, v65, v65
	v_mul_f32_e32 v145, v67, v67
	v_fmac_f32_e32 v143, v64, v64
	v_fmac_f32_e32 v145, v66, v66
	v_add_f32_e32 v143, v143, v145
	v_add_f32_e32 v128, v143, v128
	s_nop 1
	v_add_f32_dpp v128, v128, v128 quad_perm:[1,0,3,2] row_mask:0xf bank_mask:0xf
	s_nop 1
	v_add_f32_dpp v128, v128, v128 quad_perm:[2,3,0,1] row_mask:0xf bank_mask:0xf
	s_nop 1
	v_add_f32_dpp v128, v128, v128 row_half_mirror row_mask:0xf bank_mask:0xf
	s_nop 1
	v_add_f32_dpp v128, v128, v128 row_mirror row_mask:0xf bank_mask:0xf
	v_mov_b32_e32 v143, v128
	s_nop 1
	v_permlane16_swap_b32_e32 v128, v143
	v_add_f32_e32 v128, v128, v143
	v_mov_b32_e32 v143, v128
	s_nop 1
	v_permlane32_swap_b32_e32 v128, v143
	v_add_f32_e32 v128, v128, v143
	v_fmamk_f32 v128, v128, 0x3a000000, v140
	v_mul_f32_e32 v143, 0x4f800000, v128
	v_cmp_gt_f32_e32 vcc, s9, v128
	s_nop 1
	v_cndmask_b32_e32 v128, v128, v143, vcc
	v_sqrt_f32_e32 v143, v128
	s_nop 0
	v_add_u32_e32 v145, -1, v143
	v_fma_f32 v147, -v145, v143, v128
	v_cmp_ge_f32_e64 s[4:5], 0, v147
	v_add_u32_e32 v147, 1, v143
	s_nop 0
	v_cndmask_b32_e64 v145, v143, v145, s[4:5]
	v_fma_f32 v143, -v147, v143, v128
	v_cmp_lt_f32_e64 s[4:5], 0, v143
	s_nop 1
	v_cndmask_b32_e64 v143, v145, v147, s[4:5]
	v_mul_f32_e32 v145, 0x37800000, v143
	v_cndmask_b32_e32 v143, v143, v145, vcc
	v_cmp_class_f32_e32 vcc, v128, v141
	s_nop 1
	v_cndmask_b32_e32 v128, v143, v128, vcc
	v_div_scale_f32 v143, s[4:5], v128, v128, 1.0
	v_rcp_f32_e32 v145, v143
	s_nop 0
	v_fma_f32 v147, -v143, v145, 1.0
	v_fmac_f32_e32 v145, v147, v145
	v_div_scale_f32 v147, vcc, 1.0, v128, 1.0
	v_mul_f32_e32 v148, v147, v145
	v_fma_f32 v149, -v143, v148, v147
	v_fmac_f32_e32 v148, v149, v145
	v_fma_f32 v143, -v143, v148, v147
	v_div_fmas_f32 v143, v143, v145, v148
	v_div_fixup_f32 v128, v143, v128, 1.0
	s_and_saveexec_b64 s[4:5], s[0:1]
	s_cbranch_execz .LBB0_668
	s_ashr_i32 s15, s14, 31
	s_lshl_b64 s[34:35], s[14:15], 2
	s_add_u32 s34, s3, s34
	v_mul_f32_e32 v142, 0x3a000000, v142
	s_addc_u32 s35, s30, s35
	v_mov_b32_e32 v143, v128
	global_store_dwordx2 v129, v[142:143], s[34:35]
	s_branch .LBB0_668

; DI void phase_ln(Frame& F, const float* g, const float* b, bool lazy) {
;     ...
;         for (int j = 0; j < 8; ++j) { v[j] = vn[j]; s += (v[j][0] + v[j][1]) + (v[j][2] + v[j][3]); }
;         if (row + NGW < MTOK) {
; #pragma unroll
;             for (int j = 0; j < 8; ++j) vn[j] = *(const f32x4*)(xr + (size_t)NGW * DM + 256 * j); }
;         const float mean = wave_sum(s) * (1.f / DM); float s2 = 0.f;
; #pragma unroll
;         for (int j = 0; j < 8; ++j) { v[j] = v[j] - mean; s2 += (v[j][0] * v[j][0] + v[j][1] * v[j][1]) + (v[j][2] * v[j][2] + v[j][3] * v[j][3]); }
;         const float rstd = 1.f / sqrtf(wave_sum(s2) * (1.f / DM) + LN_EPS);
;         if (lazy && F.lane == 0) { lnst[2 * row] = mean; lnst[2 * row + 1] = rstd; }
.LBB0_871:
	v_add_f32_e32 v128, v124, v125
	v_add_f32_e32 v142, v126, v127
	v_add_f32_e32 v128, v128, v142
	v_add_f32_e32 v142, v120, v121
	v_add_f32_e32 v143, v122, v123
	v_add_f32_e32 v128, 0, v128
	v_add_f32_e32 v142, v142, v143
	v_add_f32_e32 v128, v142, v128
	v_add_f32_e32 v142, v116, v117
	v_add_f32_e32 v143, v118, v119
	v_add_f32_e32 v142, v142, v143
	v_add_f32_e32 v128, v142, v128
	v_add_f32_e32 v142, v80, v81
	v_add_f32_e32 v143, v82, v83
	v_add_f32_e32 v142, v142, v143
	v_add_f32_e32 v128, v142, v128
	v_add_f32_e32 v142, v76, v77
	v_add_f32_e32 v143, v78, v79
	v_add_f32_e32 v142, v142, v143
	v_add_f32_e32 v128, v142, v128
	v_add_f32_e32 v142, v72, v73
	v_add_f32_e32 v143, v74, v75
	v_add_f32_e32 v142, v142, v143
	v_add_f32_e32 v128, v142, v128
	v_add_f32_e32 v142, v68, v69
	v_add_f32_e32 v143, v70, v71
	v_add_f32_e32 v142, v142, v143
	v_add_f32_e32 v128, v142, v128
	v_add_f32_e32 v142, v64, v65
	v_add_f32_e32 v143, v66, v67
	v_add_f32_e32 v142, v142, v143
	v_add_f32_e32 v128, v142, v128
	s_nop 1
	v_add_f32_dpp v128, v128, v128 quad_perm:[1,0,3,2] row_mask:0xf bank_mask:0xf
	s_nop 1
	v_add_f32_dpp v128, v128, v128 quad_perm:[2,3,0,1] row_mask:0xf bank_mask:0xf
	s_nop 1
	v_add_f32_dpp v128, v128, v128 row_half_mirror row_mask:0xf bank_mask:0xf
	s_nop 1
	v_add_f32_dpp v128, v128, v128 row_mirror row_mask:0xf bank_mask:0xf
	v_mov_b32_e32 v142, v128
	s_nop 1
	v_permlane16_swap_b32_e32 v128, v142
	v_add_f32_e32 v128, v128, v142
	v_mov_b32_e32 v142, v128
	s_nop 1
	v_permlane32_swap_b32_e32 v128, v142
	v_add_f32_e32 v142, v128, v142
	v_fmamk_f32 v127, v142, 0xba000000, v127
	v_fmamk_f32 v125, v142, 0xba000000, v125
	v_fmamk_f32 v126, v142, 0xba000000, v126
	v_fmac_f32_e32 v124, 0xba000000, v142
	v_mul_f32_e32 v128, v125, v125
	v_mul_f32_e32 v143, v127, v127
	v_fmac_f32_e32 v128, v124, v124
	v_fmac_f32_e32 v143, v126, v126
	v_fmamk_f32 v123, v142, 0xba000000, v123
	v_fmamk_f32 v121, v142, 0xba000000, v121
	v_add_f32_e32 v128, v128, v143
	v_fmamk_f32 v122, v142, 0xba000000, v122
	v_fmac_f32_e32 v120, 0xba000000, v142
	v_mul_f32_e32 v143, v121, v121
	v_mul_f32_e32 v145, v123, v123
	v_fmac_f32_e32 v143, v120, v120
	v_fmac_f32_e32 v145, v122, v122
	v_add_f32_e32 v143, v143, v145
	v_fmamk_f32 v119, v142, 0xba000000, v119
	v_fmamk_f32 v117, v142, 0xba000000, v117
	v_add_f32_e32 v128, v128, v143
	v_fmamk_f32 v118, v142, 0xba000000, v118
	v_fmac_f32_e32 v116, 0xba000000, v142
	v_mul_f32_e32 v143, v117, v117
	v_mul_f32_e32 v145, v119, v119
	v_fmac_f32_e32 v143, v116, v116
	v_fmac_f32_e32 v145, v118, v118
	v_add_f32_e32 v143, v143, v145
	v_fmamk_f32 v83, v142, 0xba000000, v83
	v_fmamk_f32 v81, v142, 0xba000000, v81
	v_add_f32_e32 v128, v143, v128
	v_fmamk_f32 v82, v142, 0xba000000, v82
	v_fmac_f32_e32 v80, 0xba000000, v142
	v_mul_f32_e32 v143, v81, v81
	v_mul_f32_e32 v145, v83, v83
	v_fmac_f32_e32 v143, v80, v80
	v_fmac_f32_e32 v145, v82, v82
	v_add_f32_e32 v143, v143, v145
	v_fmamk_f32 v79, v142, 0xba000000, v79
	v_fmamk_f32 v77, v142, 0xba000000, v77
	v_add_f32_e32 v128, v143, v128
	v_fmamk_f32 v78, v142, 0xba000000, v78
	v_fmac_f32_e32 v76, 0xba000000, v142
	v_mul_f32_e32 v143, v77, v77
	v_mul_f32_e32 v145, v79, v79
	v_fmac_f32_e32 v143, v76, v76
	v_fmac_f32_e32 v145, v78, v78
	v_add_f32_e32 v143, v143, v145
	v_fmamk_f32 v75, v142, 0xba000000, v75
	v_fmamk_f32 v73, v142, 0xba000000, v73
	v_add_f32_e32 v128, v143, v128
	v_fmamk_f32 v74, v142, 0xba000000, v74
	v_fmac_f32_e32 v72, 0xba000000, v142
	v_mul_f32_e32 v143, v73, v73
	v_mul_f32_e32 v145, v75, v75
	v_fmac_f32_e32 v143, v72, v72
	v_fmac_f32_e32 v145, v74, v74
	v_add_f32_e32 v143, v143, v145
	v_fmamk_f32 v71, v142, 0xba000000, v71
	v_fmamk_f32 v69, v142, 0xba000000, v69
	v_add_f32_e32 v128, v143, v128
	v_fmamk_f32 v70, v142, 0xba000000, v70
	v_fmac_f32_e32 v68, 0xba000000, v142
	v_mul_f32_e32 v143, v69, v69
	v_mul_f32_e32 v145, v71, v71
	v_fmac_f32_e32 v143, v68, v68
	v_fmac_f32_e32 v145, v70, v70
	v_add_f32_e32 v143, v143, v145
	v_fmamk_f32 v67, v142, 0xba000000, v67
	v_fmamk_f32 v65, v142, 0xba000000, v65
	v_add_f32_e32 v128, v143, v128
	v_fmamk_f32 v66, v142, 0xba000000, v66
	v_fmac_f32_e32 v64, 0xba000000, v142
	v_mul_f32_e32 v143, v65, v65
	v_mul_f32_e32 v145, v67, v67
	v_fmac_f32_e32 v143, v64, v64
	v_fmac_f32_e32 v145, v66, v66
	v_add_f32_e32 v143, v143, v145
	v_add_f32_e32 v128, v143, v128
	s_nop 1
	v_add_f32_dpp v128, v128, v128 quad_perm:[1,0,3,2] row_mask:0xf bank_mask:0xf
	s_nop 1
	v_add_f32_dpp v128, v128, v128 quad_perm:[2,3,0,1] row_mask:0xf bank_mask:0xf
	s_nop 1
	v_add_f32_dpp v128, v128, v128 row_half_mirror row_mask:0xf bank_mask:0xf
	s_nop 1
	v_add_f32_dpp v128, v128, v128 row_mirror row_mask:0xf bank_mask:0xf
	v_mov_b32_e32 v143, v128
	s_nop 1
	v_permlane16_swap_b32_e32 v128, v143
	v_add_f32_e32 v128, v128, v143
	v_mov_b32_e32 v143, v128
	s_nop 1
	v_permlane32_swap_b32_e32 v128, v143
	v_add_f32_e32 v128, v128, v143
	v_fmamk_f32 v128, v128, 0x3a000000, v140
	v_mul_f32_e32 v143, 0x4f800000, v128
	v_cmp_gt_f32_e32 vcc, s9, v128
	s_nop 1
	v_cndmask_b32_e32 v128, v128, v143, vcc
	v_sqrt_f32_e32 v143, v128
	s_nop 0
	v_add_u32_e32 v145, -1, v143
	v_fma_f32 v147, -v145, v143, v128
	v_cmp_ge_f32_e64 s[4:5], 0, v147
	v_add_u32_e32 v147, 1, v143
	s_nop 0
	v_cndmask_b32_e64 v145, v143, v145, s[4:5]
	v_fma_f32 v143, -v147, v143, v128
	v_cmp_lt_f32_e64 s[4:5], 0, v143
	s_nop 1
	v_cndmask_b32_e64 v143, v145, v147, s[4:5]
	v_mul_f32_e32 v145, 0x37800000, v143
	v_cndmask_b32_e32 v143, v143, v145, vcc
	v_cmp_class_f32_e32 vcc, v128, v141
	s_nop 1
	v_cndmask_b32_e32 v128, v143, v128, vcc
	v_div_scale_f32 v143, s[4:5], v128, v128, 1.0
	v_rcp_f32_e32 v145, v143
	s_nop 0
	v_fma_f32 v147, -v143, v145, 1.0
	v_fmac_f32_e32 v145, v147, v145
	v_div_scale_f32 v147, vcc, 1.0, v128, 1.0
	v_mul_f32_e32 v148, v147, v145
	v_fma_f32 v149, -v143, v148, v147
	v_fmac_f32_e32 v148, v149, v145
	v_fma_f32 v143, -v143, v148, v147
	v_div_fmas_f32 v143, v143, v145, v148
	v_div_fixup_f32 v128, v143, v128, 1.0
	s_and_saveexec_b64 s[4:5], s[0:1]
	s_cbranch_execz .LBB0_868
	s_ashr_i32 s15, s14, 31
	s_lshl_b64 s[34:35], s[14:15], 2
	s_add_u32 s34, s3, s34
	v_mul_f32_e32 v142, 0x3a000000, v142
	s_addc_u32 s35, s30, s35
	v_mov_b32_e32 v143, v128
	global_store_dwordx2 v129, v[142:143], s[34:35]
	s_branch .LBB0_868

; DI void phase_ln(Frame& F, const float* g, const float* b, bool lazy) {
;     ...
;         for (int j = 0; j < 8; ++j) { v[j] = vn[j]; s += (v[j][0] + v[j][1]) + (v[j][2] + v[j][3]); }
;         if (row + NGW < MTOK) {
; #pragma unroll
;             for (int j = 0; j < 8; ++j) vn[j] = *(const f32x4*)(xr + (size_t)NGW * DM + 256 * j); }
;         const float mean = wave_sum(s) * (1.f / DM); float s2 = 0.f;
; #pragma unroll
;         for (int j = 0; j < 8; ++j) { v[j] = v[j] - mean; s2 += (v[j][0] * v[j][0] + v[j][1] * v[j][1]) + (v[j][2] * v[j][2] + v[j][3] * v[j][3]); }
;         const float rstd = 1.f / sqrtf(wave_sum(s2) * (1.f / DM) + LN_EPS);
;         if (lazy && F.lane == 0) { lnst[2 * row] = mean; lnst[2 * row + 1] = rstd; }
.LBB0_1332:
	v_add_f32_e32 v128, v124, v125
	v_add_f32_e32 v142, v126, v127
	v_add_f32_e32 v128, v128, v142
	v_add_f32_e32 v142, v120, v121
	v_add_f32_e32 v143, v122, v123
	v_add_f32_e32 v128, 0, v128
	v_add_f32_e32 v142, v142, v143
	v_add_f32_e32 v128, v142, v128
	v_add_f32_e32 v142, v116, v117
	v_add_f32_e32 v143, v118, v119
	v_add_f32_e32 v142, v142, v143
	v_add_f32_e32 v128, v142, v128
	v_add_f32_e32 v142, v112, v113
	v_add_f32_e32 v143, v114, v115
	v_add_f32_e32 v142, v142, v143
	v_add_f32_e32 v128, v142, v128
	v_add_f32_e32 v142, v76, v77
	v_add_f32_e32 v143, v78, v79
	v_add_f32_e32 v142, v142, v143
	v_add_f32_e32 v128, v142, v128
	v_add_f32_e32 v142, v72, v73
	v_add_f32_e32 v143, v74, v75
	v_add_f32_e32 v142, v142, v143
	v_add_f32_e32 v128, v142, v128
	v_add_f32_e32 v142, v68, v69
	v_add_f32_e32 v143, v70, v71
	v_add_f32_e32 v142, v142, v143
	v_add_f32_e32 v128, v142, v128
	v_add_f32_e32 v142, v64, v65
	v_add_f32_e32 v143, v66, v67
	v_add_f32_e32 v142, v142, v143
	v_add_f32_e32 v128, v142, v128
	s_nop 1
	v_add_f32_dpp v128, v128, v128 quad_perm:[1,0,3,2] row_mask:0xf bank_mask:0xf
	s_nop 1
	v_add_f32_dpp v128, v128, v128 quad_perm:[2,3,0,1] row_mask:0xf bank_mask:0xf
	s_nop 1
	v_add_f32_dpp v128, v128, v128 row_half_mirror row_mask:0xf bank_mask:0xf
	s_nop 1
	v_add_f32_dpp v128, v128, v128 row_mirror row_mask:0xf bank_mask:0xf
	v_mov_b32_e32 v142, v128
	s_nop 1
	v_permlane16_swap_b32_e32 v128, v142
	v_add_f32_e32 v128, v128, v142
	v_mov_b32_e32 v142, v128
	s_nop 1
	v_permlane32_swap_b32_e32 v128, v142
	v_add_f32_e32 v142, v128, v142
	v_fmamk_f32 v127, v142, 0xba000000, v127
	v_fmamk_f32 v125, v142, 0xba000000, v125
	v_fmamk_f32 v126, v142, 0xba000000, v126
	v_fmac_f32_e32 v124, 0xba000000, v142
	v_mul_f32_e32 v128, v125, v125
	v_mul_f32_e32 v143, v127, v127
	v_fmac_f32_e32 v128, v124, v124
	v_fmac_f32_e32 v143, v126, v126
	v_fmamk_f32 v123, v142, 0xba000000, v123
	v_fmamk_f32 v121, v142, 0xba000000, v121
	v_add_f32_e32 v128, v128, v143
	v_fmamk_f32 v122, v142, 0xba000000, v122
	v_fmac_f32_e32 v120, 0xba000000, v142
	v_mul_f32_e32 v143, v121, v121
	v_mul_f32_e32 v145, v123, v123
	v_fmac_f32_e32 v143, v120, v120
	v_fmac_f32_e32 v145, v122, v122
	v_add_f32_e32 v143, v143, v145
	v_fmamk_f32 v119, v142, 0xba000000, v119
	v_fmamk_f32 v117, v142, 0xba000000, v117
	v_add_f32_e32 v128, v128, v143
	v_fmamk_f32 v118, v142, 0xba000000, v118
	v_fmac_f32_e32 v116, 0xba000000, v142
	v_mul_f32_e32 v143, v117, v117
	v_mul_f32_e32 v145, v119, v119
	v_fmac_f32_e32 v143, v116, v116
	v_fmac_f32_e32 v145, v118, v118
	v_add_f32_e32 v143, v143, v145
	v_fmamk_f32 v115, v142, 0xba000000, v115
	v_fmamk_f32 v113, v142, 0xba000000, v113
	v_add_f32_e32 v128, v143, v128
	v_fmamk_f32 v114, v142, 0xba000000, v114
	v_fmac_f32_e32 v112, 0xba000000, v142
	v_mul_f32_e32 v143, v113, v113
	v_mul_f32_e32 v145, v115, v115
	v_fmac_f32_e32 v143, v112, v112
	v_fmac_f32_e32 v145, v114, v114
	v_add_f32_e32 v143, v143, v145
	v_fmamk_f32 v79, v142, 0xba000000, v79
	v_fmamk_f32 v77, v142, 0xba000000, v77
	v_add_f32_e32 v128, v143, v128
	v_fmamk_f32 v78, v142, 0xba000000, v78
	v_fmac_f32_e32 v76, 0xba000000, v142
	v_mul_f32_e32 v143, v77, v77
	v_mul_f32_e32 v145, v79, v79
	v_fmac_f32_e32 v143, v76, v76
	v_fmac_f32_e32 v145, v78, v78
	v_add_f32_e32 v143, v143, v145
	v_fmamk_f32 v75, v142, 0xba000000, v75
	v_fmamk_f32 v73, v142, 0xba000000, v73
	v_add_f32_e32 v128, v143, v128
	v_fmamk_f32 v74, v142, 0xba000000, v74
	v_fmac_f32_e32 v72, 0xba000000, v142
	v_mul_f32_e32 v143, v73, v73
	v_mul_f32_e32 v145, v75, v75
	v_fmac_f32_e32 v143, v72, v72
	v_fmac_f32_e32 v145, v74, v74
	v_add_f32_e32 v143, v143, v145
	v_fmamk_f32 v71, v142, 0xba000000, v71
	v_fmamk_f32 v69, v142, 0xba000000, v69
	v_add_f32_e32 v128, v143, v128
	v_fmamk_f32 v70, v142, 0xba000000, v70
	v_fmac_f32_e32 v68, 0xba000000, v142
	v_mul_f32_e32 v143, v69, v69
	v_mul_f32_e32 v145, v71, v71
	v_fmac_f32_e32 v143, v68, v68
	v_fmac_f32_e32 v145, v70, v70
	v_add_f32_e32 v143, v143, v145
	v_fmamk_f32 v67, v142, 0xba000000, v67
	v_fmamk_f32 v65, v142, 0xba000000, v65
	v_add_f32_e32 v128, v143, v128
	v_fmamk_f32 v66, v142, 0xba000000, v66
	v_fmac_f32_e32 v64, 0xba000000, v142
	v_mul_f32_e32 v143, v65, v65
	v_mul_f32_e32 v145, v67, v67
	v_fmac_f32_e32 v143, v64, v64
	v_fmac_f32_e32 v145, v66, v66
	v_add_f32_e32 v143, v143, v145
	v_add_f32_e32 v128, v143, v128
	s_nop 1
	v_add_f32_dpp v128, v128, v128 quad_perm:[1,0,3,2] row_mask:0xf bank_mask:0xf
	s_nop 1
	v_add_f32_dpp v128, v128, v128 quad_perm:[2,3,0,1] row_mask:0xf bank_mask:0xf
	s_nop 1
	v_add_f32_dpp v128, v128, v128 row_half_mirror row_mask:0xf bank_mask:0xf
	s_nop 1
	v_add_f32_dpp v128, v128, v128 row_mirror row_mask:0xf bank_mask:0xf
	v_mov_b32_e32 v143, v128
	s_nop 1
	v_permlane16_swap_b32_e32 v128, v143
	v_add_f32_e32 v128, v128, v143
	v_mov_b32_e32 v143, v128
	s_nop 1
	v_permlane32_swap_b32_e32 v128, v143
	v_add_f32_e32 v128, v128, v143
	v_fmamk_f32 v128, v128, 0x3a000000, v140
	v_mul_f32_e32 v143, 0x4f800000, v128
	v_cmp_gt_f32_e32 vcc, s9, v128
	s_nop 1
	v_cndmask_b32_e32 v128, v128, v143, vcc
	v_sqrt_f32_e32 v143, v128
	s_nop 0
	v_add_u32_e32 v145, -1, v143
	v_fma_f32 v147, -v145, v143, v128
	v_cmp_ge_f32_e64 s[4:5], 0, v147
	v_add_u32_e32 v147, 1, v143
	s_nop 0
	v_cndmask_b32_e64 v145, v143, v145, s[4:5]
	v_fma_f32 v143, -v147, v143, v128
	v_cmp_lt_f32_e64 s[4:5], 0, v143
	s_nop 1
	v_cndmask_b32_e64 v143, v145, v147, s[4:5]
	v_mul_f32_e32 v145, 0x37800000, v143
	v_cndmask_b32_e32 v143, v143, v145, vcc
	v_cmp_class_f32_e32 vcc, v128, v141
	s_nop 1
	v_cndmask_b32_e32 v128, v143, v128, vcc
	v_div_scale_f32 v143, s[4:5], v128, v128, 1.0
	v_rcp_f32_e32 v145, v143
	s_nop 0
	v_fma_f32 v147, -v143, v145, 1.0
	v_fmac_f32_e32 v145, v147, v145
	v_div_scale_f32 v147, vcc, 1.0, v128, 1.0
	v_mul_f32_e32 v148, v147, v145
	v_fma_f32 v149, -v143, v148, v147
	v_fmac_f32_e32 v148, v149, v145
	v_fma_f32 v143, -v143, v148, v147
	v_div_fmas_f32 v143, v143, v145, v148
	v_div_fixup_f32 v128, v143, v128, 1.0
	s_and_saveexec_b64 s[4:5], s[0:1]
	s_cbranch_execz .LBB0_1329
	s_ashr_i32 s15, s14, 31
	s_lshl_b64 s[34:35], s[14:15], 2
	s_add_u32 s34, s3, s34
	v_mul_f32_e32 v142, 0x3a000000, v142
	s_addc_u32 s35, s19, s35
	v_mov_b32_e32 v143, v128
	global_store_dwordx2 v129, v[142:143], s[34:35]
	s_branch .LBB0_1329

; DI unsigned cvtpk(float lo, float hi) { f32x2_t v = {lo, hi}; bf16x2_t b = __builtin_convertvector(v, bf16x2_t); return __builtin_bit_cast(unsigned, b); }
; DI void phase_ln(Frame& F, const float* g, const float* b, bool lazy) {
;     ...
;         for (int j = 0; j < 8; ++j) { v[j] = vn[j]; s += (v[j][0] + v[j][1]) + (v[j][2] + v[j][3]); }
;         if (row + NGW < MTOK) {
; #pragma unroll
;             for (int j = 0; j < 8; ++j) vn[j] = *(const f32x4*)(xr + (size_t)NGW * DM + 256 * j); }
;         const float mean = wave_sum(s) * (1.f / DM); float s2 = 0.f;
; #pragma unroll
;         for (int j = 0; j < 8; ++j) { v[j] = v[j] - mean; s2 += (v[j][0] * v[j][0] + v[j][1] * v[j][1]) + (v[j][2] * v[j][2] + v[j][3] * v[j][3]); }
;         const float rstd = 1.f / sqrtf(wave_sum(s2) * (1.f / DM) + LN_EPS);
;         if (lazy && F.lane == 0) { lnst[2 * row] = mean; lnst[2 * row + 1] = rstd; }
; #pragma unroll
;         for (int j = 0; j < 8; ++j) { const f32x4 y = v[j] * rstd * gv[j] + bv[j];
;             if (lazy) { u32x2 o; o.x = cvtpk(y[0], y[1]); o.y = cvtpk(y[2], y[3]); *(u32x2*)(xb + (size_t)row * DM + 256 * j + 4 * F.lane) = o; }
;             else __builtin_nontemporal_store(y, (f32x4*)(xr + 256 * j)); }
.LBB0_1529:
	v_add_f32_e32 v140, v124, v125
	v_add_f32_e32 v141, v126, v127
	v_add_f32_e32 v140, v140, v141
	v_add_f32_e32 v141, v120, v121
	v_add_f32_e32 v142, v122, v123
	v_add_f32_e32 v140, 0, v140
	v_add_f32_e32 v141, v141, v142
	v_add_f32_e32 v140, v141, v140
	v_add_f32_e32 v141, v116, v117
	v_add_f32_e32 v142, v118, v119
	v_add_f32_e32 v141, v141, v142
	v_add_f32_e32 v140, v141, v140
	v_add_f32_e32 v141, v112, v113
	v_add_f32_e32 v142, v114, v115
	v_add_f32_e32 v141, v141, v142
	v_add_f32_e32 v140, v141, v140
	v_add_f32_e32 v141, v108, v109
	v_add_f32_e32 v142, v110, v111
	v_add_f32_e32 v141, v141, v142
	v_add_f32_e32 v140, v141, v140
	v_add_f32_e32 v141, v72, v73
	v_add_f32_e32 v142, v74, v75
	v_add_f32_e32 v141, v141, v142
	v_add_f32_e32 v140, v141, v140
	v_add_f32_e32 v141, v68, v69
	v_add_f32_e32 v142, v70, v71
	v_add_f32_e32 v141, v141, v142
	v_add_f32_e32 v140, v141, v140
	v_add_f32_e32 v141, v64, v65
	v_add_f32_e32 v142, v66, v67
	v_add_f32_e32 v141, v141, v142
	v_add_f32_e32 v140, v141, v140
	s_nop 1
	v_add_f32_dpp v140, v140, v140 quad_perm:[1,0,3,2] row_mask:0xf bank_mask:0xf
	s_nop 1
	v_add_f32_dpp v140, v140, v140 quad_perm:[2,3,0,1] row_mask:0xf bank_mask:0xf
	s_nop 1
	v_add_f32_dpp v140, v140, v140 row_half_mirror row_mask:0xf bank_mask:0xf
	s_nop 1
	v_add_f32_dpp v140, v140, v140 row_mirror row_mask:0xf bank_mask:0xf
	v_mov_b32_e32 v141, v140
	s_nop 1
	v_permlane16_swap_b32_e32 v140, v141
	v_add_f32_e32 v140, v140, v141
	v_mov_b32_e32 v141, v140
	s_nop 1
	v_permlane32_swap_b32_e32 v140, v141
	v_add_f32_e32 v150, v140, v141
	v_fmamk_f32 v125, v150, 0xba000000, v125
	v_fmamk_f32 v121, v150, 0xba000000, v121
	v_fmamk_f32 v127, v150, 0xba000000, v127
	v_fmac_f32_e32 v124, 0xba000000, v150
	v_fmamk_f32 v123, v150, 0xba000000, v123
	v_fmac_f32_e32 v120, 0xba000000, v150
	v_mov_b32_e32 v142, v125
	v_mov_b32_e32 v143, v121
	v_fmamk_f32 v126, v150, 0xba000000, v126
	v_fmamk_f32 v122, v150, 0xba000000, v122
	v_mov_b32_e32 v140, v124
	v_mov_b32_e32 v141, v120
	v_pk_mul_f32 v[142:143], v[142:143], v[142:143]
	v_mov_b32_e32 v144, v127
	v_mov_b32_e32 v145, v123
	v_pk_fma_f32 v[140:141], v[140:141], v[140:141], v[142:143]
	v_mov_b32_e32 v142, v126
	v_mov_b32_e32 v143, v122
	v_pk_mul_f32 v[144:145], v[144:145], v[144:145]
	v_fmamk_f32 v117, v150, 0xba000000, v117
	v_pk_fma_f32 v[142:143], v[142:143], v[142:143], v[144:145]
	v_fmamk_f32 v116, v150, 0xba000000, v116
	v_pk_add_f32 v[140:141], v[140:141], v[142:143]
	v_fmamk_f32 v119, v150, 0xba000000, v119
	v_fmac_f32_e32 v118, 0xba000000, v150
	v_pk_add_f32 v[140:141], v[140:141], v[140:141] op_sel_hi:[0,1]
	v_pk_mul_f32 v[142:143], v[118:119], v[118:119]
	v_pk_mul_f32 v[144:145], v[116:117], v[116:117]
	v_fmamk_f32 v112, v150, 0xba000000, v112
	v_pk_mov_b32 v[146:147], v[144:145], v[142:143] op_sel:[1,0]
	v_mov_b32_e32 v145, v143
	v_fmamk_f32 v113, v150, 0xba000000, v113
	v_fmac_f32_e32 v114, 0xba000000, v150
	v_mul_f32_e32 v140, v112, v112
	v_pk_add_f32 v[142:143], v[146:147], v[144:145]
	v_fmamk_f32 v115, v150, 0xba000000, v115
	v_pk_fma_f32 v[144:145], v[112:113], v[112:113], v[140:141] op_sel_hi:[1,1,0]
	v_mul_f32_e32 v140, v114, v114
	v_pk_add_f32 v[142:143], v[142:143], v[142:143] op_sel_hi:[0,1]
	v_pk_fma_f32 v[146:147], v[114:115], v[114:115], v[140:141] op_sel_hi:[1,1,0]
	v_fmamk_f32 v111, v150, 0xba000000, v111
	v_fmamk_f32 v110, v150, 0xba000000, v110
	v_fmamk_f32 v109, v150, 0xba000000, v109
	v_fmac_f32_e32 v108, 0xba000000, v150
	v_mul_f32_e32 v144, v108, v108
	v_mul_f32_e32 v146, v109, v109
	v_mul_f32_e32 v142, v110, v110
	v_mul_f32_e32 v140, v111, v111
	v_pk_add_f32 v[144:145], v[144:145], v[146:147]
	v_pk_add_f32 v[140:141], v[142:143], v[140:141]
	v_fmamk_f32 v73, v150, 0xba000000, v73
	v_fmamk_f32 v72, v150, 0xba000000, v72
	v_fmamk_f32 v75, v150, 0xba000000, v75
	v_fmac_f32_e32 v74, 0xba000000, v150
	v_pk_add_f32 v[140:141], v[144:145], v[140:141]
	v_pk_mul_f32 v[142:143], v[74:75], v[74:75]
	v_pk_mul_f32 v[144:145], v[72:73], v[72:73]
	v_fmac_f32_e32 v70, 0xba000000, v150
	v_pk_mov_b32 v[146:147], v[144:145], v[142:143] op_sel:[1,0]
	v_mov_b32_e32 v145, v143
	v_pk_add_f32 v[142:143], v[146:147], v[144:145]
	v_fmamk_f32 v144, v150, 0xba000000, v68
	v_fmamk_f32 v145, v150, 0xba000000, v69
	v_mul_f32_e32 v68, v144, v144
	v_pk_fma_f32 v[68:69], v[144:145], v[144:145], v[68:69] op_sel_hi:[1,1,0]
	v_fmamk_f32 v71, v150, 0xba000000, v71
	v_mul_f32_e32 v68, v70, v70
	v_pk_add_f32 v[140:141], v[140:141], v[140:141] op_sel_hi:[0,1]
	v_pk_add_f32 v[142:143], v[142:143], v[142:143] op_sel_hi:[0,1]
	v_pk_fma_f32 v[146:147], v[70:71], v[70:71], v[68:69] op_sel_hi:[1,1,0]
	v_fmamk_f32 v149, v150, 0xba000000, v67
	v_fmamk_f32 v148, v150, 0xba000000, v66
	v_fmamk_f32 v65, v150, 0xba000000, v65
	v_fmac_f32_e32 v64, 0xba000000, v150
	v_mul_f32_e32 v68, v64, v64
	v_mul_f32_e32 v146, v65, v65
	v_mul_f32_e32 v142, v148, v148
	v_mul_f32_e32 v140, v149, v149
	v_pk_add_f32 v[66:67], v[68:69], v[146:147]
	v_pk_add_f32 v[68:69], v[142:143], v[140:141]
	s_nop 0
	v_pk_add_f32 v[66:67], v[66:67], v[68:69]
	s_nop 0
	v_add_f32_e32 v66, v66, v67
	s_nop 1
	v_add_f32_dpp v66, v66, v66 quad_perm:[1,0,3,2] row_mask:0xf bank_mask:0xf
	s_nop 1
	v_add_f32_dpp v66, v66, v66 quad_perm:[2,3,0,1] row_mask:0xf bank_mask:0xf
	s_nop 1
	v_add_f32_dpp v66, v66, v66 row_half_mirror row_mask:0xf bank_mask:0xf
	s_nop 1
	v_add_f32_dpp v66, v66, v66 row_mirror row_mask:0xf bank_mask:0xf
	v_mov_b32_e32 v67, v66
	s_nop 1
	v_permlane16_swap_b32_e32 v66, v67
	v_add_f32_e32 v66, v66, v67
	v_mov_b32_e32 v67, v66
	s_nop 1
	v_permlane32_swap_b32_e32 v66, v67
	v_add_f32_e32 v66, v66, v67
	v_fmamk_f32 v66, v66, 0x3a000000, v138
	v_mul_f32_e32 v67, 0x4f800000, v66
	v_cmp_gt_f32_e32 vcc, s3, v66
	s_nop 1
	v_cndmask_b32_e32 v66, v66, v67, vcc
	v_sqrt_f32_e32 v67, v66
	s_nop 0
	v_add_u32_e32 v68, -1, v67
	v_fma_f32 v69, -v68, v67, v66
	v_cmp_ge_f32_e64 s[0:1], 0, v69
	v_add_u32_e32 v69, 1, v67
	s_nop 0
	v_cndmask_b32_e64 v68, v67, v68, s[0:1]
	v_fma_f32 v67, -v69, v67, v66
	v_cmp_lt_f32_e64 s[0:1], 0, v67
	s_nop 1
	v_cndmask_b32_e64 v67, v68, v69, s[0:1]
	v_mul_f32_e32 v68, 0x37800000, v67
	v_cndmask_b32_e32 v67, v67, v68, vcc
	v_cmp_class_f32_e32 vcc, v66, v139
	s_nop 1
	v_cndmask_b32_e32 v66, v67, v66, vcc
	v_div_scale_f32 v67, s[0:1], v66, v66, 1.0
	v_rcp_f32_e32 v68, v67
	s_nop 0
	v_fma_f32 v69, -v67, v68, 1.0
	v_fmac_f32_e32 v68, v69, v68
	v_div_scale_f32 v69, vcc, 1.0, v66, 1.0
	v_mul_f32_e32 v140, v69, v68
	v_fma_f32 v141, -v67, v140, v69
	v_fmac_f32_e32 v140, v141, v68
	v_fma_f32 v67, -v67, v140, v69
	v_div_fmas_f32 v67, v67, v68, v140
	v_div_fixup_f32 v140, v67, v66, 1.0
	v_pk_mul_f32 v[66:67], v[124:125], v[140:141] op_sel_hi:[1,0]
	v_pk_mul_f32 v[68:69], v[126:127], v[140:141] op_sel_hi:[1,0]
	v_pk_fma_f32 v[66:67], v[0:1], v[66:67], v[4:5]
	v_pk_fma_f32 v[68:69], v[2:3], v[68:69], v[6:7]
	global_store_dwordx4 v[128:129], v[66:69], off offset:-4096 nt
	v_pk_mul_f32 v[64:65], v[64:65], v[140:141] op_sel_hi:[1,0]
	s_waitcnt vmcnt(8)
; DI unsigned cvtpk(float lo, float hi) { f32x2_t v = {lo, hi}; bf16x2_t b = __builtin_convertvector(v, bf16x2_t); return __builtin_bit_cast(unsigned, b); }
; DI void phase_ln(Frame& F, const float* g, const float* b, bool lazy) {
;     ...
;         for (int j = 0; j < 8; ++j) { const f32x4 y = v[j] * rstd * gv[j] + bv[j];
;             if (lazy) { u32x2 o; o.x = cvtpk(y[0], y[1]); o.y = cvtpk(y[2], y[3]); *(u32x2*)(xb + (size_t)row * DM + 256 * j + 4 * F.lane) = o; }
;             else __builtin_nontemporal_store(y, (f32x4*)(xr + 256 * j)); }
	v_mov_b64_e32 v[126:127], v[106:107]
	v_pk_mul_f32 v[66:67], v[120:121], v[140:141] op_sel_hi:[1,0]
	v_pk_mul_f32 v[68:69], v[122:123], v[140:141] op_sel_hi:[1,0]
	v_pk_fma_f32 v[66:67], v[8:9], v[66:67], v[16:17]
	v_pk_fma_f32 v[68:69], v[10:11], v[68:69], v[18:19]
	global_store_dwordx4 v[128:129], v[66:69], off offset:-3072 nt
	s_waitcnt vmcnt(2)
	v_pk_fma_f32 v[64:65], v[52:53], v[64:65], v[60:61]
	v_mov_b64_e32 v[122:123], v[102:103]
	v_pk_mul_f32 v[66:67], v[116:117], v[140:141] op_sel_hi:[1,0]
	v_pk_mul_f32 v[68:69], v[118:119], v[140:141] op_sel_hi:[1,0]
	v_pk_fma_f32 v[66:67], v[12:13], v[66:67], v[20:21]
	v_pk_fma_f32 v[68:69], v[14:15], v[68:69], v[22:23]
	global_store_dwordx4 v[128:129], v[66:69], off offset:-2048 nt
	v_mov_b64_e32 v[118:119], v[98:99]
	s_andn2_b64 vcc, exec, s[8:9]
	v_pk_mul_f32 v[66:67], v[112:113], v[140:141] op_sel_hi:[1,0]
	v_pk_mul_f32 v[68:69], v[114:115], v[140:141] op_sel_hi:[1,0]
	v_pk_fma_f32 v[66:67], v[24:25], v[66:67], v[28:29]
	v_pk_fma_f32 v[68:69], v[26:27], v[68:69], v[30:31]
	global_store_dwordx4 v[128:129], v[66:69], off offset:-1024 nt
	v_mov_b64_e32 v[114:115], v[94:95]
	v_mov_b64_e32 v[112:113], v[92:93]
	v_pk_mul_f32 v[66:67], v[108:109], v[140:141] op_sel_hi:[1,0]
	v_pk_mul_f32 v[68:69], v[110:111], v[140:141] op_sel_hi:[1,0]
	v_pk_fma_f32 v[66:67], v[32:33], v[66:67], v[40:41]
	v_pk_fma_f32 v[68:69], v[34:35], v[68:69], v[42:43]
	global_store_dwordx4 v[128:129], v[66:69], off nt
	v_mov_b64_e32 v[110:111], v[90:91]
	v_mov_b64_e32 v[108:109], v[88:89]
	v_pk_mul_f32 v[66:67], v[72:73], v[140:141] op_sel_hi:[1,0]
	v_pk_mul_f32 v[68:69], v[74:75], v[140:141] op_sel_hi:[1,0]
	v_pk_fma_f32 v[66:67], v[36:37], v[66:67], v[44:45]
	v_pk_fma_f32 v[68:69], v[38:39], v[68:69], v[46:47]
	global_store_dwordx4 v[128:129], v[66:69], off offset:1024 nt
	v_mov_b64_e32 v[72:73], v[84:85]
	v_mov_b64_e32 v[74:75], v[86:87]
	v_pk_mul_f32 v[66:67], v[144:145], v[140:141] op_sel_hi:[1,0]
	v_pk_mul_f32 v[68:69], v[70:71], v[140:141] op_sel_hi:[1,0]
	v_pk_fma_f32 v[66:67], v[48:49], v[66:67], v[56:57]
	v_pk_fma_f32 v[68:69], v[50:51], v[68:69], v[58:59]
	global_store_dwordx4 v[128:129], v[66:69], off offset:2048 nt
	v_mov_b64_e32 v[116:117], v[96:97]
	v_mov_b64_e32 v[120:121], v[100:101]
	v_pk_mul_f32 v[66:67], v[148:149], v[140:141] op_sel_hi:[1,0]
	v_mov_b64_e32 v[68:69], v[80:81]
	v_pk_fma_f32 v[66:67], v[54:55], v[66:67], v[62:63]
	global_store_dwordx4 v[128:129], v[64:67], off offset:3072 nt
	v_mov_b64_e32 v[128:129], v[130:131]
	v_mov_b64_e32 v[70:71], v[82:83]
	v_mov_b64_e32 v[64:65], v[76:77]
	v_mov_b64_e32 v[66:67], v[78:79]
	v_mov_b64_e32 v[124:125], v[104:105]
	s_cbranch_vccz .LBB0_1532
